# kprio4 + non-leader workgroups poll the cross-XCD generation word directly in the grid barrier (one hop less), measure 1
# speedup vs baseline: 1.0042x; 1.0042x over previous
; __device__ __forceinline__ unsigned xb_ld(unsigned* p)              { return __hip_atomic_load(p, __ATOMIC_RELAXED, __HIP_MEMORY_SCOPE_AGENT); }
; __device__ __forceinline__ unsigned xb_add(unsigned* p, unsigned v) { return __hip_atomic_fetch_add(p, v, __ATOMIC_RELAXED, __HIP_MEMORY_SCOPE_AGENT); }
; #define XB_SPIN(cond, bar) do { unsigned _sp = 0; while (cond) { __builtin_amdgcn_s_sleep(1); \
;     if ((++_sp & 255u) == 0u) { if (xb_ld(&(bar)[XB_TMO])) break; if (_sp > XB_SPIN_CAP) { atomicAdd(&(bar)[XB_TMO], 1u); break; } } } } while (0)
; __device__ __forceinline__ void xcd_barrier(const XcdBarrier& b) {
;     ...
;         const unsigned old = xb_add(&bar[XB_XSUB(b.x)], 1u);
;         const unsigned gen = old / nloc;
;         if (old + 1u == (gen + 1u) * nloc) {
;             __builtin_amdgcn_fence(__ATOMIC_RELEASE, "agent");
;             asm volatile("s_waitcnt vmcnt(0)" ::: "memory");
;             const unsigned og = xb_add(&bar[XB_TOP], 1u);
;             const unsigned tg = og / nx;
;             if (og + 1u == (tg + 1u) * nx) xb_add(&bar[XB_TOPGEN], 1u);
;             else XB_SPIN(xb_ld(&bar[XB_TOPGEN]) == tg, bar);
;             __builtin_amdgcn_fence(__ATOMIC_ACQUIRE, "agent");
;             xb_add(&bar[XB_XGEN(b.x)], 1u);
;             asm volatile("s_waitcnt vmcnt(0)" ::: "memory");
;         } else {
;             XB_SPIN(xb_ld(&bar[XB_XGEN(b.x)]) == gen, bar);
.LBB0_243:
	v_readlane_b32 s4, v253, 15
	v_readlane_b32 s5, v253, 16
	v_mov_b32_e32 v1, 1
	v_sub_u32_e32 v4, 0, v2
	s_nop 2
	global_atomic_add v3, v177, v1, s[4:5] sc0
	v_cvt_f32_u32_e32 v1, v2
	v_rcp_iflag_f32_e32 v1, v1
	s_nop 0
	v_mul_f32_e32 v1, 0x4f7ffffe, v1
	v_cvt_u32_f32_e32 v1, v1
	v_mul_lo_u32 v4, v4, v1
	v_mul_hi_u32 v4, v1, v4
	v_add_u32_e32 v1, v1, v4
	s_waitcnt vmcnt(0)
	v_mul_hi_u32 v1, v3, v1
	v_mul_lo_u32 v4, v1, v2
	v_sub_u32_e32 v4, v3, v4
	v_add_u32_e32 v5, 1, v1
	v_cmp_ge_u32_e32 vcc, v4, v2
	v_add_u32_e32 v3, 1, v3
	s_nop 0
	v_cndmask_b32_e32 v1, v1, v5, vcc
	v_sub_u32_e32 v5, v4, v2
	v_cndmask_b32_e32 v4, v4, v5, vcc
	v_add_u32_e32 v5, 1, v1
	v_cmp_ge_u32_e32 vcc, v4, v2
	s_nop 1
	v_cndmask_b32_e32 v1, v1, v5, vcc
	v_mul_lo_u32 v4, v2, v1
	v_add_u32_e32 v2, v4, v2
	v_cmp_ne_u32_e32 vcc, v3, v2
	s_and_saveexec_b64 s[4:5], vcc
	s_xor_b64 s[4:5], exec, s[4:5]
	s_cbranch_execz .LBB0_257
	v_readlane_b32 s6, v253, 21
	v_readlane_b32 s7, v253, 22
	s_waitcnt lgkmcnt(0)
	s_nop 3
	global_load_dword v0, v177, s[6:7] sc1
	s_waitcnt vmcnt(0)
	v_cmp_eq_u32_e32 vcc, v0, v1
	s_and_saveexec_b64 s[6:7], vcc
	s_cbranch_execz .LBB0_256
	s_mov_b32 s24, 1
	s_mov_b64 s[8:9], 0
	s_branch .LBB0_247

; __device__ __forceinline__ unsigned xb_ld(unsigned* p)              { return __hip_atomic_load(p, __ATOMIC_RELAXED, __HIP_MEMORY_SCOPE_AGENT); }
; #define XB_SPIN(cond, bar) do { unsigned _sp = 0; while (cond) { __builtin_amdgcn_s_sleep(1); \
;     if ((++_sp & 255u) == 0u) { if (xb_ld(&(bar)[XB_TMO])) break; if (_sp > XB_SPIN_CAP) { atomicAdd(&(bar)[XB_TMO], 1u); break; } } } } while (0)
; __device__ __forceinline__ void xcd_barrier(const XcdBarrier& b) {
;     ...
;             XB_SPIN(xb_ld(&bar[XB_XGEN(b.x)]) == gen, bar);
.LBB0_251:
	v_readlane_b32 s12, v253, 21
	v_readlane_b32 s13, v253, 22
	s_add_i32 s24, s24, 1
	s_mov_b64 s[14:15], -1
	s_nop 2
	global_load_dword v0, v177, s[12:13] sc1
	s_waitcnt vmcnt(0)
	v_cmp_ne_u32_e32 vcc, v0, v1
	s_orn2_b64 s[12:13], vcc, exec
	s_branch .LBB0_246

; __device__ __forceinline__ unsigned xb_ld(unsigned* p)              { return __hip_atomic_load(p, __ATOMIC_RELAXED, __HIP_MEMORY_SCOPE_AGENT); }
; __device__ __forceinline__ unsigned xb_add(unsigned* p, unsigned v) { return __hip_atomic_fetch_add(p, v, __ATOMIC_RELAXED, __HIP_MEMORY_SCOPE_AGENT); }
; #define XB_SPIN(cond, bar) do { unsigned _sp = 0; while (cond) { __builtin_amdgcn_s_sleep(1); \
;     if ((++_sp & 255u) == 0u) { if (xb_ld(&(bar)[XB_TMO])) break; if (_sp > XB_SPIN_CAP) { atomicAdd(&(bar)[XB_TMO], 1u); break; } } } } while (0)
; __device__ __forceinline__ void xcd_barrier(const XcdBarrier& b) {
;     ...
;         const unsigned old = xb_add(&bar[XB_XSUB(b.x)], 1u);
;         const unsigned gen = old / nloc;
;         if (old + 1u == (gen + 1u) * nloc) {
;             __builtin_amdgcn_fence(__ATOMIC_RELEASE, "agent");
;             asm volatile("s_waitcnt vmcnt(0)" ::: "memory");
;             const unsigned og = xb_add(&bar[XB_TOP], 1u);
;             const unsigned tg = og / nx;
;             if (og + 1u == (tg + 1u) * nx) xb_add(&bar[XB_TOPGEN], 1u);
;             else XB_SPIN(xb_ld(&bar[XB_TOPGEN]) == tg, bar);
;             __builtin_amdgcn_fence(__ATOMIC_ACQUIRE, "agent");
;             xb_add(&bar[XB_XGEN(b.x)], 1u);
;             asm volatile("s_waitcnt vmcnt(0)" ::: "memory");
;         } else {
;             XB_SPIN(xb_ld(&bar[XB_XGEN(b.x)]) == gen, bar);
.LBB0_320:
	v_readlane_b32 s6, v253, 15
	v_readlane_b32 s7, v253, 16
	v_mov_b32_e32 v1, 1
	v_sub_u32_e32 v4, 0, v2
	s_nop 2
	global_atomic_add v3, v177, v1, s[6:7] sc0
	v_cvt_f32_u32_e32 v1, v2
	v_rcp_iflag_f32_e32 v1, v1
	s_nop 0
	v_mul_f32_e32 v1, 0x4f7ffffe, v1
	v_cvt_u32_f32_e32 v1, v1
	v_mul_lo_u32 v4, v4, v1
	v_mul_hi_u32 v4, v1, v4
	v_add_u32_e32 v1, v1, v4
	s_waitcnt vmcnt(0)
	v_mul_hi_u32 v1, v3, v1
	v_mul_lo_u32 v4, v1, v2
	v_sub_u32_e32 v4, v3, v4
	v_add_u32_e32 v5, 1, v1
	v_cmp_ge_u32_e32 vcc, v4, v2
	v_add_u32_e32 v3, 1, v3
	s_nop 0
	v_cndmask_b32_e32 v1, v1, v5, vcc
	v_sub_u32_e32 v5, v4, v2
	v_cndmask_b32_e32 v4, v4, v5, vcc
	v_add_u32_e32 v5, 1, v1
	v_cmp_ge_u32_e32 vcc, v4, v2
	s_nop 1
	v_cndmask_b32_e32 v1, v1, v5, vcc
	v_mul_lo_u32 v4, v2, v1
	v_add_u32_e32 v2, v4, v2
	v_cmp_ne_u32_e32 vcc, v3, v2
	s_and_saveexec_b64 s[6:7], vcc
	s_xor_b64 s[6:7], exec, s[6:7]
	s_cbranch_execz .LBB0_334
	v_readlane_b32 s8, v253, 21
	v_readlane_b32 s9, v253, 22
	s_waitcnt lgkmcnt(0)
	s_nop 3
	global_load_dword v0, v177, s[8:9] sc1
	s_waitcnt vmcnt(0)
	v_cmp_eq_u32_e32 vcc, v0, v1
	s_and_saveexec_b64 s[8:9], vcc
	s_cbranch_execz .LBB0_333
	s_mov_b32 s26, 1
	s_mov_b64 s[10:11], 0
	s_branch .LBB0_324

; __device__ __forceinline__ unsigned xb_ld(unsigned* p)              { return __hip_atomic_load(p, __ATOMIC_RELAXED, __HIP_MEMORY_SCOPE_AGENT); }
; #define XB_SPIN(cond, bar) do { unsigned _sp = 0; while (cond) { __builtin_amdgcn_s_sleep(1); \
;     if ((++_sp & 255u) == 0u) { if (xb_ld(&(bar)[XB_TMO])) break; if (_sp > XB_SPIN_CAP) { atomicAdd(&(bar)[XB_TMO], 1u); break; } } } } while (0)
; __device__ __forceinline__ void xcd_barrier(const XcdBarrier& b) {
;     ...
;             XB_SPIN(xb_ld(&bar[XB_XGEN(b.x)]) == gen, bar);
.LBB0_328:
	v_readlane_b32 s14, v253, 21
	v_readlane_b32 s15, v253, 22
	s_add_i32 s26, s26, 1
	s_mov_b64 s[16:17], -1
	s_nop 2
	global_load_dword v0, v177, s[14:15] sc1
	s_waitcnt vmcnt(0)
	v_cmp_ne_u32_e32 vcc, v0, v1
	s_orn2_b64 s[14:15], vcc, exec
	s_branch .LBB0_323

; __device__ __forceinline__ unsigned xb_ld(unsigned* p)              { return __hip_atomic_load(p, __ATOMIC_RELAXED, __HIP_MEMORY_SCOPE_AGENT); }
; __device__ __forceinline__ unsigned xb_add(unsigned* p, unsigned v) { return __hip_atomic_fetch_add(p, v, __ATOMIC_RELAXED, __HIP_MEMORY_SCOPE_AGENT); }
; #define XB_SPIN(cond, bar) do { unsigned _sp = 0; while (cond) { __builtin_amdgcn_s_sleep(1); \
;     if ((++_sp & 255u) == 0u) { if (xb_ld(&(bar)[XB_TMO])) break; if (_sp > XB_SPIN_CAP) { atomicAdd(&(bar)[XB_TMO], 1u); break; } } } } while (0)
; __device__ __forceinline__ void xcd_barrier(const XcdBarrier& b) {
;     ...
;         const unsigned old = xb_add(&bar[XB_XSUB(b.x)], 1u);
;         const unsigned gen = old / nloc;
;         if (old + 1u == (gen + 1u) * nloc) {
;             __builtin_amdgcn_fence(__ATOMIC_RELEASE, "agent");
;             asm volatile("s_waitcnt vmcnt(0)" ::: "memory");
;             const unsigned og = xb_add(&bar[XB_TOP], 1u);
;             const unsigned tg = og / nx;
;             if (og + 1u == (tg + 1u) * nx) xb_add(&bar[XB_TOPGEN], 1u);
;             else XB_SPIN(xb_ld(&bar[XB_TOPGEN]) == tg, bar);
;             __builtin_amdgcn_fence(__ATOMIC_ACQUIRE, "agent");
;             xb_add(&bar[XB_XGEN(b.x)], 1u);
;             asm volatile("s_waitcnt vmcnt(0)" ::: "memory");
;         } else {
;             XB_SPIN(xb_ld(&bar[XB_XGEN(b.x)]) == gen, bar);
.LBB0_1219:
	v_readlane_b32 s4, v253, 15
	v_readlane_b32 s5, v253, 16
	v_mov_b32_e32 v1, 1
	v_sub_u32_e32 v4, 0, v2
	s_nop 2
	global_atomic_add v3, v177, v1, s[4:5] sc0
	v_cvt_f32_u32_e32 v1, v2
	v_rcp_iflag_f32_e32 v1, v1
	s_nop 0
	v_mul_f32_e32 v1, 0x4f7ffffe, v1
	v_cvt_u32_f32_e32 v1, v1
	v_mul_lo_u32 v4, v4, v1
	v_mul_hi_u32 v4, v1, v4
	v_add_u32_e32 v1, v1, v4
	s_waitcnt vmcnt(0)
	v_mul_hi_u32 v1, v3, v1
	v_mul_lo_u32 v4, v1, v2
	v_sub_u32_e32 v4, v3, v4
	v_add_u32_e32 v5, 1, v1
	v_cmp_ge_u32_e32 vcc, v4, v2
	v_add_u32_e32 v3, 1, v3
	s_nop 0
	v_cndmask_b32_e32 v1, v1, v5, vcc
	v_sub_u32_e32 v5, v4, v2
	v_cndmask_b32_e32 v4, v4, v5, vcc
	v_add_u32_e32 v5, 1, v1
	v_cmp_ge_u32_e32 vcc, v4, v2
	s_nop 1
	v_cndmask_b32_e32 v1, v1, v5, vcc
	v_mul_lo_u32 v4, v2, v1
	v_add_u32_e32 v2, v4, v2
	v_cmp_ne_u32_e32 vcc, v3, v2
	s_and_saveexec_b64 s[4:5], vcc
	s_xor_b64 s[4:5], exec, s[4:5]
	s_cbranch_execz .LBB0_1233
	v_readlane_b32 s6, v253, 21
	v_readlane_b32 s7, v253, 22
	s_waitcnt lgkmcnt(0)
	s_nop 3
	global_load_dword v0, v177, s[6:7] sc1
	s_waitcnt vmcnt(0)
	v_cmp_eq_u32_e32 vcc, v0, v1
	s_and_saveexec_b64 s[6:7], vcc
	s_cbranch_execz .LBB0_1232
	s_mov_b32 s18, 1
	s_mov_b64 s[8:9], 0
	s_branch .LBB0_1223

; __device__ __forceinline__ unsigned xb_ld(unsigned* p)              { return __hip_atomic_load(p, __ATOMIC_RELAXED, __HIP_MEMORY_SCOPE_AGENT); }
; #define XB_SPIN(cond, bar) do { unsigned _sp = 0; while (cond) { __builtin_amdgcn_s_sleep(1); \
;     if ((++_sp & 255u) == 0u) { if (xb_ld(&(bar)[XB_TMO])) break; if (_sp > XB_SPIN_CAP) { atomicAdd(&(bar)[XB_TMO], 1u); break; } } } } while (0)
; __device__ __forceinline__ void xcd_barrier(const XcdBarrier& b) {
;     ...
;             XB_SPIN(xb_ld(&bar[XB_XGEN(b.x)]) == gen, bar);
.LBB0_1227:
	v_readlane_b32 s12, v253, 21
	v_readlane_b32 s13, v253, 22
	s_add_i32 s18, s18, 1
	s_mov_b64 s[14:15], -1
	s_nop 2
	global_load_dword v0, v177, s[12:13] sc1
	s_waitcnt vmcnt(0)
	v_cmp_ne_u32_e32 vcc, v0, v1
	s_orn2_b64 s[12:13], vcc, exec
	s_branch .LBB0_1222
